# w_o residual epilogue fused with the rmsnorm+modulate phase that followed it (deterministic row sums, 4-workgroup meeting); that norm phase and one grid barrier removed; on the final-norm fusion
# baseline (speedup 1.0000x reference)
.LBB0_1131:
	s_lshl_b32 s0, s87, 9
	v_add_u32_e32 v0, s0, v230
	v_mov_b32_e32 v1, 0x200
	v_cmp_gt_u32_e32 vcc, v1, v0
	s_and_saveexec_b64 s[2:3], vcc
	s_load_dwordx2 s[0:1], s[92:93], 0xd8
	v_lshlrev_b32_e32 v0, 2, v0
	v_mov_b32_e32 v1, 0
	s_waitcnt lgkmcnt(0)
	s_add_u32 s0, s0, 0x33a0000
	s_addc_u32 s1, s1, 0
	global_store_dword v0, v1, s[0:1]
	s_or_b64 exec, exec, s[2:3]
	s_waitcnt vmcnt(0)
	s_barrier
	s_mov_b64 s[0:1], exec
	v_readlane_b32 s2, v252, 2
	v_readlane_b32 s3, v252, 3
	s_and_b64 s[2:3], s[0:1], s[2:3]
	s_mov_b64 exec, s[2:3]
	s_cbranch_execz .LBB0_1183
	s_add_i32 s2, 0, 0x20040
	v_mov_b32_e32 v0, s2
	s_waitcnt vmcnt(0) expcnt(0) lgkmcnt(0)
	ds_read_b32 v2, v0
	s_add_i32 s2, 0, 0x20044
	v_mov_b32_e32 v0, s2
	ds_read_b32 v0, v0
	s_waitcnt lgkmcnt(1)
	v_cmp_ne_u32_e32 vcc, 0, v2
	s_cbranch_vccnz .LBB0_1147
	s_add_u32 s6, s88, 0x1000
	s_addc_u32 s7, s89, 0
	s_add_u32 s8, s88, 0x1100
	s_addc_u32 s9, s89, 0
	s_add_u32 s10, s88, 0x1200
	v_readlane_b32 s2, v252, 0
	s_addc_u32 s11, s89, 0
	s_mul_i32 s2, s91, s2
	s_add_u32 s12, s88, 0x1300
	s_mul_i32 s2, s2, s90
	s_addc_u32 s13, s89, 0
	s_mov_b32 s3, 1
	v_mov_b32_e32 v16, 0
	s_branch .LBB0_1135

.LBB0_1203:
	s_mov_b32 s40, s38
	s_mov_b32 s41, s39
	v_lshl_add_u32 v128, s38, 8, v206
	v_lshl_or_b32 v136, s39, 8, v208
	s_load_dwordx2 s[42:43], s[92:93], 0xa8
	s_load_dwordx2 s[44:45], s[92:93], 0xd8
	s_ashr_i32 s2, s38, 4
	v_lshlrev_b32_e32 v136, 2, v136
	s_mul_hi_i32 s15, s2, 0x9000
	s_mul_i32 s2, s2, 0x9000
	v_lshl_add_u32 v128, v128, 12, v136
	s_add_u32 s38, s58, s2
	s_addc_u32 s39, s59, s15
	v_add_u32_e32 v129, 0x10000, v128
	v_add_u32_e32 v130, 0x20000, v128
	v_add_u32_e32 v131, 0x30000, v128
	v_add_u32_e32 v132, 0x80000, v128
	v_add_u32_e32 v133, 0x90000, v128
	v_add_u32_e32 v134, 0xa0000, v128
	v_add_u32_e32 v135, 0xb0000, v128
	v_and_b32_e32 v137, 63, v230
	v_xor_b32_e32 v138, 32, v137
	v_xor_b32_e32 v137, 16, v137
	v_lshlrev_b32_e32 v138, 2, v138
	v_lshlrev_b32_e32 v137, 2, v137
	global_load_dwordx4 v[140:143], v136, s[38:39]
	global_load_dwordx4 v[144:147], v136, s[38:39] offset:64
	global_load_dwordx4 v[148:151], v136, s[38:39] offset:512
	global_load_dwordx4 v[152:155], v136, s[38:39] offset:576
	global_load_dwordx4 v[180:183], v128, s[8:9]
	global_load_dwordx4 v[184:187], v128, s[8:9] offset:64
	global_load_dwordx4 v[188:191], v128, s[8:9] offset:512
	global_load_dwordx4 v[192:195], v128, s[8:9] offset:576
	global_load_dwordx4 v[196:199], v129, s[8:9]
	global_load_dwordx4 v[200:203], v129, s[8:9] offset:64
	global_load_dwordx4 v[212:215], v129, s[8:9] offset:512
	global_load_dwordx4 v[216:219], v129, s[8:9] offset:576
	global_load_dwordx4 v[220:223], v130, s[8:9]
	global_load_dwordx4 v[224:227], v130, s[8:9] offset:64
	global_load_dwordx4 v[232:235], v130, s[8:9] offset:512
	global_load_dwordx4 v[236:239], v130, s[8:9] offset:576
	global_load_dwordx4 v[240:243], v131, s[8:9]
	global_load_dwordx4 v[244:247], v131, s[8:9] offset:64
	global_load_dwordx4 v[156:159], v131, s[8:9] offset:512
	global_load_dwordx4 v[160:163], v131, s[8:9] offset:576
	s_waitcnt lgkmcnt(0)
	s_add_u32 s66, s44, 0x3010000
	s_addc_u32 s67, s45, 0
	s_add_u32 s66, s66, s2
	s_addc_u32 s67, s67, s15
	s_add_u32 s70, s66, 0x7000
	s_addc_u32 s71, s67, 0
	s_add_u32 s72, s66, 0x6000
	s_addc_u32 s73, s67, 0
	s_add_u32 s68, s44, 0x86a0000
	s_addc_u32 s69, s45, 0
	s_add_u32 s44, s44, 0x32a0000
	s_addc_u32 s45, s45, 0
	s_add_u32 s46, s44, 0x100000
	s_addc_u32 s47, s45, 0
	s_waitcnt vmcnt(8)
	v_pk_fma_f32 v[124:125], v[124:125], v[140:141], v[180:181]
	v_pk_fma_f32 v[126:127], v[126:127], v[142:143], v[182:183]
	v_pk_mul_f32 v[248:249], v[124:125], v[124:125]
	v_pk_fma_f32 v[248:249], v[126:127], v[126:127], v[248:249]
	v_pk_fma_f32 v[100:101], v[100:101], v[144:145], v[184:185]
	v_pk_fma_f32 v[102:103], v[102:103], v[146:147], v[186:187]
	v_pk_fma_f32 v[248:249], v[100:101], v[100:101], v[248:249]
	v_pk_fma_f32 v[248:249], v[102:103], v[102:103], v[248:249]
	v_pk_fma_f32 v[68:69], v[68:69], v[148:149], v[188:189]
	v_pk_fma_f32 v[70:71], v[70:71], v[150:151], v[190:191]
	v_pk_fma_f32 v[248:249], v[68:69], v[68:69], v[248:249]
	v_pk_fma_f32 v[248:249], v[70:71], v[70:71], v[248:249]
	v_pk_fma_f32 v[44:45], v[44:45], v[152:153], v[192:193]
	v_pk_fma_f32 v[46:47], v[46:47], v[154:155], v[194:195]
	v_pk_fma_f32 v[248:249], v[44:45], v[44:45], v[248:249]
	v_pk_fma_f32 v[248:249], v[46:47], v[46:47], v[248:249]
	global_store_dwordx4 v128, v[124:127], s[8:9]
	global_store_dwordx4 v128, v[100:103], s[8:9] offset:64
	global_store_dwordx4 v128, v[68:71], s[8:9] offset:512
	global_store_dwordx4 v128, v[44:47], s[8:9] offset:576
	v_add_f32_e32 v164, v248, v249
	v_pk_fma_f32 v[120:121], v[120:121], v[140:141], v[196:197]
	v_pk_fma_f32 v[122:123], v[122:123], v[142:143], v[198:199]
	v_pk_mul_f32 v[248:249], v[120:121], v[120:121]
	v_pk_fma_f32 v[248:249], v[122:123], v[122:123], v[248:249]
	v_pk_fma_f32 v[96:97], v[96:97], v[144:145], v[200:201]
	v_pk_fma_f32 v[98:99], v[98:99], v[146:147], v[202:203]
	v_pk_fma_f32 v[248:249], v[96:97], v[96:97], v[248:249]
	v_pk_fma_f32 v[248:249], v[98:99], v[98:99], v[248:249]
	v_pk_fma_f32 v[64:65], v[64:65], v[148:149], v[212:213]
	v_pk_fma_f32 v[66:67], v[66:67], v[150:151], v[214:215]
	v_pk_fma_f32 v[248:249], v[64:65], v[64:65], v[248:249]
	v_pk_fma_f32 v[248:249], v[66:67], v[66:67], v[248:249]
	v_pk_fma_f32 v[36:37], v[36:37], v[152:153], v[216:217]
	v_pk_fma_f32 v[38:39], v[38:39], v[154:155], v[218:219]
	v_pk_fma_f32 v[248:249], v[36:37], v[36:37], v[248:249]
	v_pk_fma_f32 v[248:249], v[38:39], v[38:39], v[248:249]
	global_store_dwordx4 v129, v[120:123], s[8:9]
	global_store_dwordx4 v129, v[96:99], s[8:9] offset:64
	global_store_dwordx4 v129, v[64:67], s[8:9] offset:512
	global_store_dwordx4 v129, v[36:39], s[8:9] offset:576
	v_add_f32_e32 v165, v248, v249
	s_nop 1
	global_load_dwordx4 v[180:183], v132, s[8:9]
	global_load_dwordx4 v[184:187], v132, s[8:9] offset:64
	global_load_dwordx4 v[188:191], v132, s[8:9] offset:512
	global_load_dwordx4 v[192:195], v132, s[8:9] offset:576
	global_load_dwordx4 v[196:199], v133, s[8:9]
	global_load_dwordx4 v[200:203], v133, s[8:9] offset:64
	global_load_dwordx4 v[212:215], v133, s[8:9] offset:512
	global_load_dwordx4 v[216:219], v133, s[8:9] offset:576
	s_waitcnt vmcnt(16)
	v_pk_fma_f32 v[116:117], v[116:117], v[140:141], v[220:221]
	v_pk_fma_f32 v[118:119], v[118:119], v[142:143], v[222:223]
	v_pk_mul_f32 v[248:249], v[116:117], v[116:117]
	v_pk_fma_f32 v[248:249], v[118:119], v[118:119], v[248:249]
	v_pk_fma_f32 v[88:89], v[88:89], v[144:145], v[224:225]
	v_pk_fma_f32 v[90:91], v[90:91], v[146:147], v[226:227]
	v_pk_fma_f32 v[248:249], v[88:89], v[88:89], v[248:249]
	v_pk_fma_f32 v[248:249], v[90:91], v[90:91], v[248:249]
	v_pk_fma_f32 v[52:53], v[52:53], v[148:149], v[232:233]
	v_pk_fma_f32 v[54:55], v[54:55], v[150:151], v[234:235]
	v_pk_fma_f32 v[248:249], v[52:53], v[52:53], v[248:249]
	v_pk_fma_f32 v[248:249], v[54:55], v[54:55], v[248:249]
	v_pk_fma_f32 v[28:29], v[28:29], v[152:153], v[236:237]
	v_pk_fma_f32 v[30:31], v[30:31], v[154:155], v[238:239]
	v_pk_fma_f32 v[248:249], v[28:29], v[28:29], v[248:249]
	v_pk_fma_f32 v[248:249], v[30:31], v[30:31], v[248:249]
	global_store_dwordx4 v130, v[116:119], s[8:9]
	global_store_dwordx4 v130, v[88:91], s[8:9] offset:64
	global_store_dwordx4 v130, v[52:55], s[8:9] offset:512
	global_store_dwordx4 v130, v[28:31], s[8:9] offset:576
	v_add_f32_e32 v166, v248, v249
	v_pk_fma_f32 v[112:113], v[112:113], v[140:141], v[240:241]
	v_pk_fma_f32 v[114:115], v[114:115], v[142:143], v[242:243]
	v_pk_mul_f32 v[248:249], v[112:113], v[112:113]
	v_pk_fma_f32 v[248:249], v[114:115], v[114:115], v[248:249]
	v_pk_fma_f32 v[80:81], v[80:81], v[144:145], v[244:245]
	v_pk_fma_f32 v[82:83], v[82:83], v[146:147], v[246:247]
	v_pk_fma_f32 v[248:249], v[80:81], v[80:81], v[248:249]
	v_pk_fma_f32 v[248:249], v[82:83], v[82:83], v[248:249]
	v_pk_fma_f32 v[48:49], v[48:49], v[148:149], v[156:157]
	v_pk_fma_f32 v[50:51], v[50:51], v[150:151], v[158:159]
	v_pk_fma_f32 v[248:249], v[48:49], v[48:49], v[248:249]
	v_pk_fma_f32 v[248:249], v[50:51], v[50:51], v[248:249]
	v_pk_fma_f32 v[20:21], v[20:21], v[152:153], v[160:161]
	v_pk_fma_f32 v[22:23], v[22:23], v[154:155], v[162:163]
	v_pk_fma_f32 v[248:249], v[20:21], v[20:21], v[248:249]
	v_pk_fma_f32 v[248:249], v[22:23], v[22:23], v[248:249]
	global_store_dwordx4 v131, v[112:115], s[8:9]
	global_store_dwordx4 v131, v[80:83], s[8:9] offset:64
	global_store_dwordx4 v131, v[48:51], s[8:9] offset:512
	global_store_dwordx4 v131, v[20:23], s[8:9] offset:576
	v_add_f32_e32 v167, v248, v249
	s_nop 1
	global_load_dwordx4 v[220:223], v134, s[8:9]
	global_load_dwordx4 v[224:227], v134, s[8:9] offset:64
	global_load_dwordx4 v[232:235], v134, s[8:9] offset:512
	global_load_dwordx4 v[236:239], v134, s[8:9] offset:576
	global_load_dwordx4 v[240:243], v135, s[8:9]
	global_load_dwordx4 v[244:247], v135, s[8:9] offset:64
	global_load_dwordx4 v[156:159], v135, s[8:9] offset:512
	global_load_dwordx4 v[160:163], v135, s[8:9] offset:576
	s_waitcnt vmcnt(16)
	v_pk_fma_f32 v[108:109], v[108:109], v[140:141], v[180:181]
	v_pk_fma_f32 v[110:111], v[110:111], v[142:143], v[182:183]
	v_pk_mul_f32 v[248:249], v[108:109], v[108:109]
	v_pk_fma_f32 v[248:249], v[110:111], v[110:111], v[248:249]
	v_pk_fma_f32 v[76:77], v[76:77], v[144:145], v[184:185]
	v_pk_fma_f32 v[78:79], v[78:79], v[146:147], v[186:187]
	v_pk_fma_f32 v[248:249], v[76:77], v[76:77], v[248:249]
	v_pk_fma_f32 v[248:249], v[78:79], v[78:79], v[248:249]
	v_pk_fma_f32 v[40:41], v[40:41], v[148:149], v[188:189]
	v_pk_fma_f32 v[42:43], v[42:43], v[150:151], v[190:191]
	v_pk_fma_f32 v[248:249], v[40:41], v[40:41], v[248:249]
	v_pk_fma_f32 v[248:249], v[42:43], v[42:43], v[248:249]
	v_pk_fma_f32 v[12:13], v[12:13], v[152:153], v[192:193]
	v_pk_fma_f32 v[14:15], v[14:15], v[154:155], v[194:195]
	v_pk_fma_f32 v[248:249], v[12:13], v[12:13], v[248:249]
	v_pk_fma_f32 v[248:249], v[14:15], v[14:15], v[248:249]
	global_store_dwordx4 v132, v[108:111], s[8:9]
	global_store_dwordx4 v132, v[76:79], s[8:9] offset:64
	global_store_dwordx4 v132, v[40:43], s[8:9] offset:512
	global_store_dwordx4 v132, v[12:15], s[8:9] offset:576
	v_add_f32_e32 v204, v248, v249
	v_pk_fma_f32 v[104:105], v[104:105], v[140:141], v[196:197]
	v_pk_fma_f32 v[106:107], v[106:107], v[142:143], v[198:199]
	v_pk_mul_f32 v[248:249], v[104:105], v[104:105]
	v_pk_fma_f32 v[248:249], v[106:107], v[106:107], v[248:249]
	v_pk_fma_f32 v[72:73], v[72:73], v[144:145], v[200:201]
	v_pk_fma_f32 v[74:75], v[74:75], v[146:147], v[202:203]
	v_pk_fma_f32 v[248:249], v[72:73], v[72:73], v[248:249]
	v_pk_fma_f32 v[248:249], v[74:75], v[74:75], v[248:249]
	v_pk_fma_f32 v[32:33], v[32:33], v[148:149], v[212:213]
	v_pk_fma_f32 v[34:35], v[34:35], v[150:151], v[214:215]
	v_pk_fma_f32 v[248:249], v[32:33], v[32:33], v[248:249]
	v_pk_fma_f32 v[248:249], v[34:35], v[34:35], v[248:249]
	v_pk_fma_f32 v[8:9], v[8:9], v[152:153], v[216:217]
	v_pk_fma_f32 v[10:11], v[10:11], v[154:155], v[218:219]
	v_pk_fma_f32 v[248:249], v[8:9], v[8:9], v[248:249]
	v_pk_fma_f32 v[248:249], v[10:11], v[10:11], v[248:249]
	global_store_dwordx4 v133, v[104:107], s[8:9]
	global_store_dwordx4 v133, v[72:75], s[8:9] offset:64
	global_store_dwordx4 v133, v[32:35], s[8:9] offset:512
	global_store_dwordx4 v133, v[8:11], s[8:9] offset:576
	v_add_f32_e32 v205, v248, v249
	s_waitcnt vmcnt(8)
	v_pk_fma_f32 v[92:93], v[92:93], v[140:141], v[220:221]
	v_pk_fma_f32 v[94:95], v[94:95], v[142:143], v[222:223]
	v_pk_mul_f32 v[248:249], v[92:93], v[92:93]
	v_pk_fma_f32 v[248:249], v[94:95], v[94:95], v[248:249]
	v_pk_fma_f32 v[60:61], v[60:61], v[144:145], v[224:225]
	v_pk_fma_f32 v[62:63], v[62:63], v[146:147], v[226:227]
	v_pk_fma_f32 v[248:249], v[60:61], v[60:61], v[248:249]
	v_pk_fma_f32 v[248:249], v[62:63], v[62:63], v[248:249]
	v_pk_fma_f32 v[24:25], v[24:25], v[148:149], v[232:233]
	v_pk_fma_f32 v[26:27], v[26:27], v[150:151], v[234:235]
	v_pk_fma_f32 v[248:249], v[24:25], v[24:25], v[248:249]
	v_pk_fma_f32 v[248:249], v[26:27], v[26:27], v[248:249]
	v_pk_fma_f32 v[4:5], v[4:5], v[152:153], v[236:237]
	v_pk_fma_f32 v[6:7], v[6:7], v[154:155], v[238:239]
	v_pk_fma_f32 v[248:249], v[4:5], v[4:5], v[248:249]
	v_pk_fma_f32 v[248:249], v[6:7], v[6:7], v[248:249]
	global_store_dwordx4 v134, v[92:95], s[8:9]
	global_store_dwordx4 v134, v[60:63], s[8:9] offset:64
	global_store_dwordx4 v134, v[24:27], s[8:9] offset:512
	global_store_dwordx4 v134, v[4:7], s[8:9] offset:576
	v_add_f32_e32 v228, v248, v249
	v_pk_fma_f32 v[84:85], v[84:85], v[140:141], v[240:241]
	v_pk_fma_f32 v[86:87], v[86:87], v[142:143], v[242:243]
	v_pk_mul_f32 v[248:249], v[84:85], v[84:85]
	v_pk_fma_f32 v[248:249], v[86:87], v[86:87], v[248:249]
	v_pk_fma_f32 v[56:57], v[56:57], v[144:145], v[244:245]
	v_pk_fma_f32 v[58:59], v[58:59], v[146:147], v[246:247]
	v_pk_fma_f32 v[248:249], v[56:57], v[56:57], v[248:249]
	v_pk_fma_f32 v[248:249], v[58:59], v[58:59], v[248:249]
	v_pk_fma_f32 v[16:17], v[16:17], v[148:149], v[156:157]
	v_pk_fma_f32 v[18:19], v[18:19], v[150:151], v[158:159]
	v_pk_fma_f32 v[248:249], v[16:17], v[16:17], v[248:249]
	v_pk_fma_f32 v[248:249], v[18:19], v[18:19], v[248:249]
	v_pk_fma_f32 v[0:1], v[0:1], v[152:153], v[160:161]
	v_pk_fma_f32 v[2:3], v[2:3], v[154:155], v[162:163]
	v_pk_fma_f32 v[248:249], v[0:1], v[0:1], v[248:249]
	v_pk_fma_f32 v[248:249], v[2:3], v[2:3], v[248:249]
	global_store_dwordx4 v135, v[84:87], s[8:9]
	global_store_dwordx4 v135, v[56:59], s[8:9] offset:64
	global_store_dwordx4 v135, v[16:19], s[8:9] offset:512
	global_store_dwordx4 v135, v[0:3], s[8:9] offset:576
	v_add_f32_e32 v229, v248, v249
	ds_bpermute_b32 v180, v137, v164
	ds_bpermute_b32 v181, v137, v165
	ds_bpermute_b32 v182, v137, v166
	ds_bpermute_b32 v183, v137, v167
	ds_bpermute_b32 v184, v137, v204
	ds_bpermute_b32 v185, v137, v205
	ds_bpermute_b32 v186, v137, v228
	ds_bpermute_b32 v187, v137, v229
	s_waitcnt lgkmcnt(0)
	v_add_f32_e32 v164, v164, v180
	v_add_f32_e32 v165, v165, v181
	v_add_f32_e32 v166, v166, v182
	v_add_f32_e32 v167, v167, v183
	v_add_f32_e32 v204, v204, v184
	v_add_f32_e32 v205, v205, v185
	v_add_f32_e32 v228, v228, v186
	v_add_f32_e32 v229, v229, v187
	ds_bpermute_b32 v180, v138, v164
	ds_bpermute_b32 v181, v138, v165
	ds_bpermute_b32 v182, v138, v166
	ds_bpermute_b32 v183, v138, v167
	ds_bpermute_b32 v184, v138, v204
	ds_bpermute_b32 v185, v138, v205
	ds_bpermute_b32 v186, v138, v228
	ds_bpermute_b32 v187, v138, v229
	s_waitcnt lgkmcnt(0)
	v_add_f32_e32 v164, v164, v180
	v_add_f32_e32 v165, v165, v181
	v_add_f32_e32 v166, v166, v182
	v_add_f32_e32 v167, v167, v183
	v_add_f32_e32 v204, v204, v184
	v_add_f32_e32 v205, v205, v185
	v_add_f32_e32 v228, v228, v186
	v_add_f32_e32 v229, v229, v187
	v_lshrrev_b32_e32 v140, 5, v208
	v_and_b32_e32 v140, 3, v140
	v_lshlrev_b32_e32 v142, 4, v206
	v_add_u32_e32 v142, 0x20400, v142
	v_lshl_add_u32 v141, v140, 2, v142
	v_lshl_add_u32 v144, s40, 8, v206
	v_lshlrev_b32_e32 v144, 4, v144
	v_mov_b32_e32 v143, s41
	v_lshl_add_u32 v143, v143, 2, v144
	s_mov_b64 exec, 0xffff
	ds_write_b32 v141, v164
	ds_write_b32 v141, v165 offset:256
	ds_write_b32 v141, v166 offset:512
	ds_write_b32 v141, v167 offset:768
	ds_write_b32 v141, v204 offset:2048
	ds_write_b32 v141, v205 offset:2304
	ds_write_b32 v141, v228 offset:2560
	ds_write_b32 v141, v229 offset:2816
	s_mov_b64 exec, -1
	s_waitcnt lgkmcnt(0)
	s_barrier
	ds_read_b128 v[220:223], v142
	ds_read_b128 v[224:227], v142 offset:256
	ds_read_b128 v[232:235], v142 offset:512
	ds_read_b128 v[236:239], v142 offset:768
	ds_read_b128 v[240:243], v142 offset:2048
	ds_read_b128 v[244:247], v142 offset:2304
	ds_read_b128 v[156:159], v142 offset:2560
	ds_read_b128 v[160:163], v142 offset:2816
	s_waitcnt lgkmcnt(0)
	v_add_f32_e32 v248, v220, v221
	v_add_f32_e32 v249, v222, v223
	v_add_f32_e32 v164, v248, v249
	v_add_f32_e32 v248, v224, v225
	v_add_f32_e32 v249, v226, v227
	v_add_f32_e32 v165, v248, v249
	v_add_f32_e32 v248, v232, v233
	v_add_f32_e32 v249, v234, v235
	v_add_f32_e32 v166, v248, v249
	v_add_f32_e32 v248, v236, v237
	v_add_f32_e32 v249, v238, v239
	v_add_f32_e32 v167, v248, v249
	v_add_f32_e32 v248, v240, v241
	v_add_f32_e32 v249, v242, v243
	v_add_f32_e32 v204, v248, v249
	v_add_f32_e32 v248, v244, v245
	v_add_f32_e32 v249, v246, v247
	v_add_f32_e32 v205, v248, v249
	v_add_f32_e32 v248, v156, v157
	v_add_f32_e32 v249, v158, v159
	v_add_f32_e32 v228, v248, v249
	v_add_f32_e32 v248, v160, v161
	v_add_f32_e32 v249, v162, v163
	v_add_f32_e32 v229, v248, v249
	v_readfirstlane_b32 s24, v140
	s_nop 0
	s_cmp_lg_u32 s24, 0
	s_cbranch_scc1 .Lfn_nosw_p11
	s_mov_b64 exec, 0xffff
	global_atomic_swap v143, v164, s[44:45]
	global_atomic_swap v143, v165, s[44:45] offset:256
	global_atomic_swap v143, v166, s[44:45] offset:512
	global_atomic_swap v143, v167, s[44:45] offset:768
	global_atomic_swap v143, v204, s[44:45] offset:2048
	global_atomic_swap v143, v205, s[44:45] offset:2304
	global_atomic_swap v143, v228, s[44:45] offset:2560
	global_atomic_swap v143, v229, s[44:45] offset:2816
	s_mov_b64 exec, -1
.Lfn_nosw_p11:
	s_waitcnt vmcnt(0)
	s_barrier
	v_cmp_eq_u32_e32 vcc, 0, v230
	s_and_saveexec_b64 s[22:23], vcc
	s_cbranch_execz .Lfn_meet_p11
	s_lshl_b32 s24, s40, 2
	v_mov_b32_e32 v248, 1
	v_mov_b32_e32 v249, s24
	s_mov_b32 s25, 0
	global_atomic_add v249, v248, s[46:47]
.Lfn_spin_p11:
	global_load_dword v248, v249, s[46:47] sc1
	s_waitcnt vmcnt(0)
	v_readfirstlane_b32 s24, v248
	s_add_i32 s25, s25, 1
	s_cmp_ge_u32 s24, 4
	s_cbranch_scc1 .Lfn_meet_p11
	s_sleep 1
	s_cmp_lt_u32 s25, 0x8000
	s_cbranch_scc1 .Lfn_spin_p11
.Lfn_meet_p11:
	s_or_b64 exec, exec, s[22:23]
	s_barrier
	global_load_dwordx4 v[220:223], v144, s[44:45] sc1
	global_load_dwordx4 v[224:227], v144, s[44:45] offset:256 sc1
	global_load_dwordx4 v[232:235], v144, s[44:45] offset:512 sc1
	global_load_dwordx4 v[236:239], v144, s[44:45] offset:768 sc1
	global_load_dwordx4 v[240:243], v144, s[44:45] offset:2048 sc1
	global_load_dwordx4 v[244:247], v144, s[44:45] offset:2304 sc1
	global_load_dwordx4 v[156:159], v144, s[44:45] offset:2560 sc1
	global_load_dwordx4 v[160:163], v144, s[44:45] offset:2816 sc1
	s_waitcnt vmcnt(0)
	v_add_f32_e32 v248, v220, v221
	v_add_f32_e32 v249, v222, v223
	v_add_f32_e32 v146, v248, v249
	v_add_f32_e32 v248, v224, v225
	v_add_f32_e32 v249, v226, v227
	v_add_f32_e32 v147, v248, v249
	v_add_f32_e32 v248, v232, v233
	v_add_f32_e32 v249, v234, v235
	v_add_f32_e32 v148, v248, v249
	v_add_f32_e32 v248, v236, v237
	v_add_f32_e32 v249, v238, v239
	v_add_f32_e32 v149, v248, v249
	v_add_f32_e32 v248, v240, v241
	v_add_f32_e32 v249, v242, v243
	v_add_f32_e32 v150, v248, v249
	v_add_f32_e32 v248, v244, v245
	v_add_f32_e32 v249, v246, v247
	v_add_f32_e32 v151, v248, v249
	v_add_f32_e32 v248, v156, v157
	v_add_f32_e32 v249, v158, v159
	v_add_f32_e32 v152, v248, v249
	v_add_f32_e32 v248, v160, v161
	v_add_f32_e32 v249, v162, v163
	v_add_f32_e32 v153, v248, v249
	global_load_dwordx4 v[180:183], v136, s[42:43]
	global_load_dwordx4 v[184:187], v136, s[42:43] offset:64
	global_load_dwordx4 v[188:191], v136, s[42:43] offset:512
	global_load_dwordx4 v[192:195], v136, s[42:43] offset:576
	global_load_dwordx4 v[220:223], v136, s[70:71]
	global_load_dwordx4 v[224:227], v136, s[70:71] offset:64
	global_load_dwordx4 v[232:235], v136, s[70:71] offset:512
	global_load_dwordx4 v[236:239], v136, s[70:71] offset:576
	global_load_dwordx4 v[240:243], v136, s[72:73]
	global_load_dwordx4 v[244:247], v136, s[72:73] offset:64
	global_load_dwordx4 v[156:159], v136, s[72:73] offset:512
	global_load_dwordx4 v[160:163], v136, s[72:73] offset:576
	v_mov_b32_e32 v228, 0x358637bd
	v_mov_b32_e32 v229, 0x260
	s_mov_b32 s14, 0xf800000
	v_fmamk_f32 v146, v146, 0x3a800000, v228
	v_mul_f32_e32 v164, 0x4f800000, v146
	v_cmp_gt_f32_e32 vcc, s14, v146
	s_nop 1
	v_cndmask_b32_e32 v146, v146, v164, vcc
	v_sqrt_f32_e32 v165, v146
	s_nop 1
	v_add_u32_e32 v166, -1, v165
	v_add_u32_e32 v167, 1, v165
	v_fma_f32 v204, -v166, v165, v146
	v_fma_f32 v205, -v167, v165, v146
	v_cmp_ge_f32_e64 s[26:27], 0, v204
	s_nop 1
	v_cndmask_b32_e64 v165, v165, v166, s[26:27]
	v_cmp_lt_f32_e64 s[26:27], 0, v205
	s_nop 1
	v_cndmask_b32_e64 v165, v165, v167, s[26:27]
	v_mul_f32_e32 v166, 0x37800000, v165
	v_cndmask_b32_e32 v165, v165, v166, vcc
	v_cmp_class_f32_e32 vcc, v146, v229
	s_nop 1
	v_cndmask_b32_e32 v146, v165, v146, vcc
	v_div_scale_f32 v164, s[26:27], v146, v146, 1.0
	v_rcp_f32_e32 v165, v164
	v_div_scale_f32 v166, vcc, 1.0, v146, 1.0
	v_fma_f32 v167, -v164, v165, 1.0
	v_fmac_f32_e32 v165, v167, v165
	v_mul_f32_e32 v167, v166, v165
	v_fma_f32 v204, -v164, v167, v166
	v_fmac_f32_e32 v167, v204, v165
	v_fma_f32 v164, -v164, v167, v166
	v_div_fmas_f32 v167, v164, v165, v167
	v_div_fixup_f32 v196, v167, v146, 1.0
	v_fmamk_f32 v147, v147, 0x3a800000, v228
	v_mul_f32_e32 v164, 0x4f800000, v147
	v_cmp_gt_f32_e32 vcc, s14, v147
	s_nop 1
	v_cndmask_b32_e32 v147, v147, v164, vcc
	v_sqrt_f32_e32 v165, v147
	s_nop 1
	v_add_u32_e32 v166, -1, v165
	v_add_u32_e32 v167, 1, v165
	v_fma_f32 v204, -v166, v165, v147
	v_fma_f32 v205, -v167, v165, v147
	v_cmp_ge_f32_e64 s[26:27], 0, v204
	s_nop 1
	v_cndmask_b32_e64 v165, v165, v166, s[26:27]
	v_cmp_lt_f32_e64 s[26:27], 0, v205
	s_nop 1
	v_cndmask_b32_e64 v165, v165, v167, s[26:27]
	v_mul_f32_e32 v166, 0x37800000, v165
	v_cndmask_b32_e32 v165, v165, v166, vcc
	v_cmp_class_f32_e32 vcc, v147, v229
	s_nop 1
	v_cndmask_b32_e32 v147, v165, v147, vcc
	v_div_scale_f32 v164, s[26:27], v147, v147, 1.0
	v_rcp_f32_e32 v165, v164
	v_div_scale_f32 v166, vcc, 1.0, v147, 1.0
	v_fma_f32 v167, -v164, v165, 1.0
	v_fmac_f32_e32 v165, v167, v165
	v_mul_f32_e32 v167, v166, v165
	v_fma_f32 v204, -v164, v167, v166
	v_fmac_f32_e32 v167, v204, v165
	v_fma_f32 v164, -v164, v167, v166
	v_div_fmas_f32 v167, v164, v165, v167
	v_div_fixup_f32 v198, v167, v147, 1.0
	v_fmamk_f32 v148, v148, 0x3a800000, v228
	v_mul_f32_e32 v164, 0x4f800000, v148
	v_cmp_gt_f32_e32 vcc, s14, v148
	s_nop 1
	v_cndmask_b32_e32 v148, v148, v164, vcc
	v_sqrt_f32_e32 v165, v148
	s_nop 1
	v_add_u32_e32 v166, -1, v165
	v_add_u32_e32 v167, 1, v165
	v_fma_f32 v204, -v166, v165, v148
	v_fma_f32 v205, -v167, v165, v148
	v_cmp_ge_f32_e64 s[26:27], 0, v204
	s_nop 1
	v_cndmask_b32_e64 v165, v165, v166, s[26:27]
	v_cmp_lt_f32_e64 s[26:27], 0, v205
	s_nop 1
	v_cndmask_b32_e64 v165, v165, v167, s[26:27]
	v_mul_f32_e32 v166, 0x37800000, v165
	v_cndmask_b32_e32 v165, v165, v166, vcc
	v_cmp_class_f32_e32 vcc, v148, v229
	s_nop 1
	v_cndmask_b32_e32 v148, v165, v148, vcc
	v_div_scale_f32 v164, s[26:27], v148, v148, 1.0
	v_rcp_f32_e32 v165, v164
	v_div_scale_f32 v166, vcc, 1.0, v148, 1.0
	v_fma_f32 v167, -v164, v165, 1.0
	v_fmac_f32_e32 v165, v167, v165
	v_mul_f32_e32 v167, v166, v165
	v_fma_f32 v204, -v164, v167, v166
	v_fmac_f32_e32 v167, v204, v165
	v_fma_f32 v164, -v164, v167, v166
	v_div_fmas_f32 v167, v164, v165, v167
	v_div_fixup_f32 v200, v167, v148, 1.0
	v_fmamk_f32 v149, v149, 0x3a800000, v228
	v_mul_f32_e32 v164, 0x4f800000, v149
	v_cmp_gt_f32_e32 vcc, s14, v149
	s_nop 1
	v_cndmask_b32_e32 v149, v149, v164, vcc
	v_sqrt_f32_e32 v165, v149
	s_nop 1
	v_add_u32_e32 v166, -1, v165
	v_add_u32_e32 v167, 1, v165
	v_fma_f32 v204, -v166, v165, v149
	v_fma_f32 v205, -v167, v165, v149
	v_cmp_ge_f32_e64 s[26:27], 0, v204
	s_nop 1
	v_cndmask_b32_e64 v165, v165, v166, s[26:27]
	v_cmp_lt_f32_e64 s[26:27], 0, v205
	s_nop 1
	v_cndmask_b32_e64 v165, v165, v167, s[26:27]
	v_mul_f32_e32 v166, 0x37800000, v165
	v_cndmask_b32_e32 v165, v165, v166, vcc
	v_cmp_class_f32_e32 vcc, v149, v229
	s_nop 1
	v_cndmask_b32_e32 v149, v165, v149, vcc
	v_div_scale_f32 v164, s[26:27], v149, v149, 1.0
	v_rcp_f32_e32 v165, v164
	v_div_scale_f32 v166, vcc, 1.0, v149, 1.0
	v_fma_f32 v167, -v164, v165, 1.0
	v_fmac_f32_e32 v165, v167, v165
	v_mul_f32_e32 v167, v166, v165
	v_fma_f32 v204, -v164, v167, v166
	v_fmac_f32_e32 v167, v204, v165
	v_fma_f32 v164, -v164, v167, v166
	v_div_fmas_f32 v167, v164, v165, v167
	v_div_fixup_f32 v202, v167, v149, 1.0
	v_fmamk_f32 v150, v150, 0x3a800000, v228
	v_mul_f32_e32 v164, 0x4f800000, v150
	v_cmp_gt_f32_e32 vcc, s14, v150
	s_nop 1
	v_cndmask_b32_e32 v150, v150, v164, vcc
	v_sqrt_f32_e32 v165, v150
	s_nop 1
	v_add_u32_e32 v166, -1, v165
	v_add_u32_e32 v167, 1, v165
	v_fma_f32 v204, -v166, v165, v150
	v_fma_f32 v205, -v167, v165, v150
	v_cmp_ge_f32_e64 s[26:27], 0, v204
	s_nop 1
	v_cndmask_b32_e64 v165, v165, v166, s[26:27]
	v_cmp_lt_f32_e64 s[26:27], 0, v205
	s_nop 1
	v_cndmask_b32_e64 v165, v165, v167, s[26:27]
	v_mul_f32_e32 v166, 0x37800000, v165
	v_cndmask_b32_e32 v165, v165, v166, vcc
	v_cmp_class_f32_e32 vcc, v150, v229
	s_nop 1
	v_cndmask_b32_e32 v150, v165, v150, vcc
	v_div_scale_f32 v164, s[26:27], v150, v150, 1.0
	v_rcp_f32_e32 v165, v164
	v_div_scale_f32 v166, vcc, 1.0, v150, 1.0
	v_fma_f32 v167, -v164, v165, 1.0
	v_fmac_f32_e32 v165, v167, v165
	v_mul_f32_e32 v167, v166, v165
	v_fma_f32 v204, -v164, v167, v166
	v_fmac_f32_e32 v167, v204, v165
	v_fma_f32 v164, -v164, v167, v166
	v_div_fmas_f32 v167, v164, v165, v167
	v_div_fixup_f32 v212, v167, v150, 1.0
	v_fmamk_f32 v151, v151, 0x3a800000, v228
	v_mul_f32_e32 v164, 0x4f800000, v151
	v_cmp_gt_f32_e32 vcc, s14, v151
	s_nop 1
	v_cndmask_b32_e32 v151, v151, v164, vcc
	v_sqrt_f32_e32 v165, v151
	s_nop 1
	v_add_u32_e32 v166, -1, v165
	v_add_u32_e32 v167, 1, v165
	v_fma_f32 v204, -v166, v165, v151
	v_fma_f32 v205, -v167, v165, v151
	v_cmp_ge_f32_e64 s[26:27], 0, v204
	s_nop 1
	v_cndmask_b32_e64 v165, v165, v166, s[26:27]
	v_cmp_lt_f32_e64 s[26:27], 0, v205
	s_nop 1
	v_cndmask_b32_e64 v165, v165, v167, s[26:27]
	v_mul_f32_e32 v166, 0x37800000, v165
	v_cndmask_b32_e32 v165, v165, v166, vcc
	v_cmp_class_f32_e32 vcc, v151, v229
	s_nop 1
	v_cndmask_b32_e32 v151, v165, v151, vcc
	v_div_scale_f32 v164, s[26:27], v151, v151, 1.0
	v_rcp_f32_e32 v165, v164
	v_div_scale_f32 v166, vcc, 1.0, v151, 1.0
	v_fma_f32 v167, -v164, v165, 1.0
	v_fmac_f32_e32 v165, v167, v165
	v_mul_f32_e32 v167, v166, v165
	v_fma_f32 v204, -v164, v167, v166
	v_fmac_f32_e32 v167, v204, v165
	v_fma_f32 v164, -v164, v167, v166
	v_div_fmas_f32 v167, v164, v165, v167
	v_div_fixup_f32 v214, v167, v151, 1.0
	v_fmamk_f32 v152, v152, 0x3a800000, v228
	v_mul_f32_e32 v164, 0x4f800000, v152
	v_cmp_gt_f32_e32 vcc, s14, v152
	s_nop 1
	v_cndmask_b32_e32 v152, v152, v164, vcc
	v_sqrt_f32_e32 v165, v152
	s_nop 1
	v_add_u32_e32 v166, -1, v165
	v_add_u32_e32 v167, 1, v165
	v_fma_f32 v204, -v166, v165, v152
	v_fma_f32 v205, -v167, v165, v152
	v_cmp_ge_f32_e64 s[26:27], 0, v204
	s_nop 1
	v_cndmask_b32_e64 v165, v165, v166, s[26:27]
	v_cmp_lt_f32_e64 s[26:27], 0, v205
	s_nop 1
	v_cndmask_b32_e64 v165, v165, v167, s[26:27]
	v_mul_f32_e32 v166, 0x37800000, v165
	v_cndmask_b32_e32 v165, v165, v166, vcc
	v_cmp_class_f32_e32 vcc, v152, v229
	s_nop 1
	v_cndmask_b32_e32 v152, v165, v152, vcc
	v_div_scale_f32 v164, s[26:27], v152, v152, 1.0
	v_rcp_f32_e32 v165, v164
	v_div_scale_f32 v166, vcc, 1.0, v152, 1.0
	v_fma_f32 v167, -v164, v165, 1.0
	v_fmac_f32_e32 v165, v167, v165
	v_mul_f32_e32 v167, v166, v165
	v_fma_f32 v204, -v164, v167, v166
	v_fmac_f32_e32 v167, v204, v165
	v_fma_f32 v164, -v164, v167, v166
	v_div_fmas_f32 v167, v164, v165, v167
	v_div_fixup_f32 v216, v167, v152, 1.0
	v_fmamk_f32 v153, v153, 0x3a800000, v228
	v_mul_f32_e32 v164, 0x4f800000, v153
	v_cmp_gt_f32_e32 vcc, s14, v153
	s_nop 1
	v_cndmask_b32_e32 v153, v153, v164, vcc
	v_sqrt_f32_e32 v165, v153
	s_nop 1
	v_add_u32_e32 v166, -1, v165
	v_add_u32_e32 v167, 1, v165
	v_fma_f32 v204, -v166, v165, v153
	v_fma_f32 v205, -v167, v165, v153
	v_cmp_ge_f32_e64 s[26:27], 0, v204
	s_nop 1
	v_cndmask_b32_e64 v165, v165, v166, s[26:27]
	v_cmp_lt_f32_e64 s[26:27], 0, v205
	s_nop 1
	v_cndmask_b32_e64 v165, v165, v167, s[26:27]
	v_mul_f32_e32 v166, 0x37800000, v165
	v_cndmask_b32_e32 v165, v165, v166, vcc
	v_cmp_class_f32_e32 vcc, v153, v229
	s_nop 1
	v_cndmask_b32_e32 v153, v165, v153, vcc
	v_div_scale_f32 v164, s[26:27], v153, v153, 1.0
	v_rcp_f32_e32 v165, v164
	v_div_scale_f32 v166, vcc, 1.0, v153, 1.0
	v_fma_f32 v167, -v164, v165, 1.0
	v_fmac_f32_e32 v165, v167, v165
	v_mul_f32_e32 v167, v166, v165
	v_fma_f32 v204, -v164, v167, v166
	v_fmac_f32_e32 v167, v204, v165
	v_fma_f32 v164, -v164, v167, v166
	v_div_fmas_f32 v167, v164, v165, v167
	v_div_fixup_f32 v218, v167, v153, 1.0
	v_lshrrev_b32_e32 v128, 1, v128
	v_lshrrev_b32_e32 v129, 1, v129
	v_lshrrev_b32_e32 v130, 1, v130
	v_lshrrev_b32_e32 v131, 1, v131
	v_lshrrev_b32_e32 v132, 1, v132
	v_lshrrev_b32_e32 v133, 1, v133
	v_lshrrev_b32_e32 v134, 1, v134
	v_lshrrev_b32_e32 v135, 1, v135
	s_waitcnt vmcnt(0)
	v_pk_add_f32 v[220:221], v[220:221], 1.0 op_sel_hi:[1,0]
	v_pk_add_f32 v[222:223], v[222:223], 1.0 op_sel_hi:[1,0]
	v_pk_add_f32 v[224:225], v[224:225], 1.0 op_sel_hi:[1,0]
	v_pk_add_f32 v[226:227], v[226:227], 1.0 op_sel_hi:[1,0]
	v_pk_add_f32 v[232:233], v[232:233], 1.0 op_sel_hi:[1,0]
	v_pk_add_f32 v[234:235], v[234:235], 1.0 op_sel_hi:[1,0]
	v_pk_add_f32 v[236:237], v[236:237], 1.0 op_sel_hi:[1,0]
	v_pk_add_f32 v[238:239], v[238:239], 1.0 op_sel_hi:[1,0]
	v_pk_mul_f32 v[124:125], v[124:125], v[196:197] op_sel_hi:[1,0]
	v_pk_mul_f32 v[126:127], v[126:127], v[196:197] op_sel_hi:[1,0]
	v_pk_mul_f32 v[124:125], v[180:181], v[124:125]
	v_pk_mul_f32 v[126:127], v[182:183], v[126:127]
	v_pk_fma_f32 v[124:125], v[220:221], v[124:125], v[240:241]
	v_pk_fma_f32 v[126:127], v[222:223], v[126:127], v[242:243]
	v_cvt_pk_bf16_f32 v124, v124, v125
	v_cvt_pk_bf16_f32 v125, v126, v127
	v_pk_mul_f32 v[100:101], v[100:101], v[196:197] op_sel_hi:[1,0]
	v_pk_mul_f32 v[102:103], v[102:103], v[196:197] op_sel_hi:[1,0]
	v_pk_mul_f32 v[100:101], v[184:185], v[100:101]
	v_pk_mul_f32 v[102:103], v[186:187], v[102:103]
	v_pk_fma_f32 v[100:101], v[224:225], v[100:101], v[244:245]
	v_pk_fma_f32 v[102:103], v[226:227], v[102:103], v[246:247]
	v_cvt_pk_bf16_f32 v100, v100, v101
	v_cvt_pk_bf16_f32 v101, v102, v103
	v_pk_mul_f32 v[68:69], v[68:69], v[196:197] op_sel_hi:[1,0]
	v_pk_mul_f32 v[70:71], v[70:71], v[196:197] op_sel_hi:[1,0]
	v_pk_mul_f32 v[68:69], v[188:189], v[68:69]
	v_pk_mul_f32 v[70:71], v[190:191], v[70:71]
	v_pk_fma_f32 v[68:69], v[232:233], v[68:69], v[156:157]
	v_pk_fma_f32 v[70:71], v[234:235], v[70:71], v[158:159]
	v_cvt_pk_bf16_f32 v68, v68, v69
	v_cvt_pk_bf16_f32 v69, v70, v71
	v_pk_mul_f32 v[44:45], v[44:45], v[196:197] op_sel_hi:[1,0]
	v_pk_mul_f32 v[46:47], v[46:47], v[196:197] op_sel_hi:[1,0]
	v_pk_mul_f32 v[44:45], v[192:193], v[44:45]
	v_pk_mul_f32 v[46:47], v[194:195], v[46:47]
	v_pk_fma_f32 v[44:45], v[236:237], v[44:45], v[160:161]
	v_pk_fma_f32 v[46:47], v[238:239], v[46:47], v[162:163]
	v_cvt_pk_bf16_f32 v44, v44, v45
	v_cvt_pk_bf16_f32 v45, v46, v47
	global_store_dwordx2 v128, v[124:125], s[68:69]
	global_store_dwordx2 v128, v[100:101], s[68:69] offset:32
	global_store_dwordx2 v128, v[68:69], s[68:69] offset:256
	global_store_dwordx2 v128, v[44:45], s[68:69] offset:288
	v_pk_mul_f32 v[120:121], v[120:121], v[198:199] op_sel_hi:[1,0]
	v_pk_mul_f32 v[122:123], v[122:123], v[198:199] op_sel_hi:[1,0]
	v_pk_mul_f32 v[120:121], v[180:181], v[120:121]
	v_pk_mul_f32 v[122:123], v[182:183], v[122:123]
	v_pk_fma_f32 v[120:121], v[220:221], v[120:121], v[240:241]
	v_pk_fma_f32 v[122:123], v[222:223], v[122:123], v[242:243]
	v_cvt_pk_bf16_f32 v120, v120, v121
	v_cvt_pk_bf16_f32 v121, v122, v123
	v_pk_mul_f32 v[96:97], v[96:97], v[198:199] op_sel_hi:[1,0]
	v_pk_mul_f32 v[98:99], v[98:99], v[198:199] op_sel_hi:[1,0]
	v_pk_mul_f32 v[96:97], v[184:185], v[96:97]
	v_pk_mul_f32 v[98:99], v[186:187], v[98:99]
	v_pk_fma_f32 v[96:97], v[224:225], v[96:97], v[244:245]
	v_pk_fma_f32 v[98:99], v[226:227], v[98:99], v[246:247]
	v_cvt_pk_bf16_f32 v96, v96, v97
	v_cvt_pk_bf16_f32 v97, v98, v99
	v_pk_mul_f32 v[64:65], v[64:65], v[198:199] op_sel_hi:[1,0]
	v_pk_mul_f32 v[66:67], v[66:67], v[198:199] op_sel_hi:[1,0]
	v_pk_mul_f32 v[64:65], v[188:189], v[64:65]
	v_pk_mul_f32 v[66:67], v[190:191], v[66:67]
	v_pk_fma_f32 v[64:65], v[232:233], v[64:65], v[156:157]
	v_pk_fma_f32 v[66:67], v[234:235], v[66:67], v[158:159]
	v_cvt_pk_bf16_f32 v64, v64, v65
	v_cvt_pk_bf16_f32 v65, v66, v67
	v_pk_mul_f32 v[36:37], v[36:37], v[198:199] op_sel_hi:[1,0]
	v_pk_mul_f32 v[38:39], v[38:39], v[198:199] op_sel_hi:[1,0]
	v_pk_mul_f32 v[36:37], v[192:193], v[36:37]
	v_pk_mul_f32 v[38:39], v[194:195], v[38:39]
	v_pk_fma_f32 v[36:37], v[236:237], v[36:37], v[160:161]
	v_pk_fma_f32 v[38:39], v[238:239], v[38:39], v[162:163]
	v_cvt_pk_bf16_f32 v36, v36, v37
	v_cvt_pk_bf16_f32 v37, v38, v39
	global_store_dwordx2 v129, v[120:121], s[68:69]
	global_store_dwordx2 v129, v[96:97], s[68:69] offset:32
	global_store_dwordx2 v129, v[64:65], s[68:69] offset:256
	global_store_dwordx2 v129, v[36:37], s[68:69] offset:288
	v_pk_mul_f32 v[116:117], v[116:117], v[200:201] op_sel_hi:[1,0]
	v_pk_mul_f32 v[118:119], v[118:119], v[200:201] op_sel_hi:[1,0]
	v_pk_mul_f32 v[116:117], v[180:181], v[116:117]
	v_pk_mul_f32 v[118:119], v[182:183], v[118:119]
	v_pk_fma_f32 v[116:117], v[220:221], v[116:117], v[240:241]
	v_pk_fma_f32 v[118:119], v[222:223], v[118:119], v[242:243]
	v_cvt_pk_bf16_f32 v116, v116, v117
	v_cvt_pk_bf16_f32 v117, v118, v119
	v_pk_mul_f32 v[88:89], v[88:89], v[200:201] op_sel_hi:[1,0]
	v_pk_mul_f32 v[90:91], v[90:91], v[200:201] op_sel_hi:[1,0]
	v_pk_mul_f32 v[88:89], v[184:185], v[88:89]
	v_pk_mul_f32 v[90:91], v[186:187], v[90:91]
	v_pk_fma_f32 v[88:89], v[224:225], v[88:89], v[244:245]
	v_pk_fma_f32 v[90:91], v[226:227], v[90:91], v[246:247]
	v_cvt_pk_bf16_f32 v88, v88, v89
	v_cvt_pk_bf16_f32 v89, v90, v91
	v_pk_mul_f32 v[52:53], v[52:53], v[200:201] op_sel_hi:[1,0]
	v_pk_mul_f32 v[54:55], v[54:55], v[200:201] op_sel_hi:[1,0]
	v_pk_mul_f32 v[52:53], v[188:189], v[52:53]
	v_pk_mul_f32 v[54:55], v[190:191], v[54:55]
	v_pk_fma_f32 v[52:53], v[232:233], v[52:53], v[156:157]
	v_pk_fma_f32 v[54:55], v[234:235], v[54:55], v[158:159]
	v_cvt_pk_bf16_f32 v52, v52, v53
	v_cvt_pk_bf16_f32 v53, v54, v55
	v_pk_mul_f32 v[28:29], v[28:29], v[200:201] op_sel_hi:[1,0]
	v_pk_mul_f32 v[30:31], v[30:31], v[200:201] op_sel_hi:[1,0]
	v_pk_mul_f32 v[28:29], v[192:193], v[28:29]
	v_pk_mul_f32 v[30:31], v[194:195], v[30:31]
	v_pk_fma_f32 v[28:29], v[236:237], v[28:29], v[160:161]
	v_pk_fma_f32 v[30:31], v[238:239], v[30:31], v[162:163]
	v_cvt_pk_bf16_f32 v28, v28, v29
	v_cvt_pk_bf16_f32 v29, v30, v31
	global_store_dwordx2 v130, v[116:117], s[68:69]
	global_store_dwordx2 v130, v[88:89], s[68:69] offset:32
	global_store_dwordx2 v130, v[52:53], s[68:69] offset:256
	global_store_dwordx2 v130, v[28:29], s[68:69] offset:288
	v_pk_mul_f32 v[112:113], v[112:113], v[202:203] op_sel_hi:[1,0]
	v_pk_mul_f32 v[114:115], v[114:115], v[202:203] op_sel_hi:[1,0]
	v_pk_mul_f32 v[112:113], v[180:181], v[112:113]
	v_pk_mul_f32 v[114:115], v[182:183], v[114:115]
	v_pk_fma_f32 v[112:113], v[220:221], v[112:113], v[240:241]
	v_pk_fma_f32 v[114:115], v[222:223], v[114:115], v[242:243]
	v_cvt_pk_bf16_f32 v112, v112, v113
	v_cvt_pk_bf16_f32 v113, v114, v115
	v_pk_mul_f32 v[80:81], v[80:81], v[202:203] op_sel_hi:[1,0]
	v_pk_mul_f32 v[82:83], v[82:83], v[202:203] op_sel_hi:[1,0]
	v_pk_mul_f32 v[80:81], v[184:185], v[80:81]
	v_pk_mul_f32 v[82:83], v[186:187], v[82:83]
	v_pk_fma_f32 v[80:81], v[224:225], v[80:81], v[244:245]
	v_pk_fma_f32 v[82:83], v[226:227], v[82:83], v[246:247]
	v_cvt_pk_bf16_f32 v80, v80, v81
	v_cvt_pk_bf16_f32 v81, v82, v83
	v_pk_mul_f32 v[48:49], v[48:49], v[202:203] op_sel_hi:[1,0]
	v_pk_mul_f32 v[50:51], v[50:51], v[202:203] op_sel_hi:[1,0]
	v_pk_mul_f32 v[48:49], v[188:189], v[48:49]
	v_pk_mul_f32 v[50:51], v[190:191], v[50:51]
	v_pk_fma_f32 v[48:49], v[232:233], v[48:49], v[156:157]
	v_pk_fma_f32 v[50:51], v[234:235], v[50:51], v[158:159]
	v_cvt_pk_bf16_f32 v48, v48, v49
	v_cvt_pk_bf16_f32 v49, v50, v51
	v_pk_mul_f32 v[20:21], v[20:21], v[202:203] op_sel_hi:[1,0]
	v_pk_mul_f32 v[22:23], v[22:23], v[202:203] op_sel_hi:[1,0]
	v_pk_mul_f32 v[20:21], v[192:193], v[20:21]
	v_pk_mul_f32 v[22:23], v[194:195], v[22:23]
	v_pk_fma_f32 v[20:21], v[236:237], v[20:21], v[160:161]
	v_pk_fma_f32 v[22:23], v[238:239], v[22:23], v[162:163]
	v_cvt_pk_bf16_f32 v20, v20, v21
	v_cvt_pk_bf16_f32 v21, v22, v23
	global_store_dwordx2 v131, v[112:113], s[68:69]
	global_store_dwordx2 v131, v[80:81], s[68:69] offset:32
	global_store_dwordx2 v131, v[48:49], s[68:69] offset:256
	global_store_dwordx2 v131, v[20:21], s[68:69] offset:288
	v_pk_mul_f32 v[108:109], v[108:109], v[212:213] op_sel_hi:[1,0]
	v_pk_mul_f32 v[110:111], v[110:111], v[212:213] op_sel_hi:[1,0]
	v_pk_mul_f32 v[108:109], v[180:181], v[108:109]
	v_pk_mul_f32 v[110:111], v[182:183], v[110:111]
	v_pk_fma_f32 v[108:109], v[220:221], v[108:109], v[240:241]
	v_pk_fma_f32 v[110:111], v[222:223], v[110:111], v[242:243]
	v_cvt_pk_bf16_f32 v108, v108, v109
	v_cvt_pk_bf16_f32 v109, v110, v111
	v_pk_mul_f32 v[76:77], v[76:77], v[212:213] op_sel_hi:[1,0]
	v_pk_mul_f32 v[78:79], v[78:79], v[212:213] op_sel_hi:[1,0]
	v_pk_mul_f32 v[76:77], v[184:185], v[76:77]
	v_pk_mul_f32 v[78:79], v[186:187], v[78:79]
	v_pk_fma_f32 v[76:77], v[224:225], v[76:77], v[244:245]
	v_pk_fma_f32 v[78:79], v[226:227], v[78:79], v[246:247]
	v_cvt_pk_bf16_f32 v76, v76, v77
	v_cvt_pk_bf16_f32 v77, v78, v79
	v_pk_mul_f32 v[40:41], v[40:41], v[212:213] op_sel_hi:[1,0]
	v_pk_mul_f32 v[42:43], v[42:43], v[212:213] op_sel_hi:[1,0]
	v_pk_mul_f32 v[40:41], v[188:189], v[40:41]
	v_pk_mul_f32 v[42:43], v[190:191], v[42:43]
	v_pk_fma_f32 v[40:41], v[232:233], v[40:41], v[156:157]
	v_pk_fma_f32 v[42:43], v[234:235], v[42:43], v[158:159]
	v_cvt_pk_bf16_f32 v40, v40, v41
	v_cvt_pk_bf16_f32 v41, v42, v43
	v_pk_mul_f32 v[12:13], v[12:13], v[212:213] op_sel_hi:[1,0]
	v_pk_mul_f32 v[14:15], v[14:15], v[212:213] op_sel_hi:[1,0]
	v_pk_mul_f32 v[12:13], v[192:193], v[12:13]
	v_pk_mul_f32 v[14:15], v[194:195], v[14:15]
	v_pk_fma_f32 v[12:13], v[236:237], v[12:13], v[160:161]
	v_pk_fma_f32 v[14:15], v[238:239], v[14:15], v[162:163]
	v_cvt_pk_bf16_f32 v12, v12, v13
	v_cvt_pk_bf16_f32 v13, v14, v15
	global_store_dwordx2 v132, v[108:109], s[68:69]
	global_store_dwordx2 v132, v[76:77], s[68:69] offset:32
	global_store_dwordx2 v132, v[40:41], s[68:69] offset:256
	global_store_dwordx2 v132, v[12:13], s[68:69] offset:288
	v_pk_mul_f32 v[104:105], v[104:105], v[214:215] op_sel_hi:[1,0]
	v_pk_mul_f32 v[106:107], v[106:107], v[214:215] op_sel_hi:[1,0]
	v_pk_mul_f32 v[104:105], v[180:181], v[104:105]
	v_pk_mul_f32 v[106:107], v[182:183], v[106:107]
	v_pk_fma_f32 v[104:105], v[220:221], v[104:105], v[240:241]
	v_pk_fma_f32 v[106:107], v[222:223], v[106:107], v[242:243]
	v_cvt_pk_bf16_f32 v104, v104, v105
	v_cvt_pk_bf16_f32 v105, v106, v107
	v_pk_mul_f32 v[72:73], v[72:73], v[214:215] op_sel_hi:[1,0]
	v_pk_mul_f32 v[74:75], v[74:75], v[214:215] op_sel_hi:[1,0]
	v_pk_mul_f32 v[72:73], v[184:185], v[72:73]
	v_pk_mul_f32 v[74:75], v[186:187], v[74:75]
	v_pk_fma_f32 v[72:73], v[224:225], v[72:73], v[244:245]
	v_pk_fma_f32 v[74:75], v[226:227], v[74:75], v[246:247]
	v_cvt_pk_bf16_f32 v72, v72, v73
	v_cvt_pk_bf16_f32 v73, v74, v75
	v_pk_mul_f32 v[32:33], v[32:33], v[214:215] op_sel_hi:[1,0]
	v_pk_mul_f32 v[34:35], v[34:35], v[214:215] op_sel_hi:[1,0]
	v_pk_mul_f32 v[32:33], v[188:189], v[32:33]
	v_pk_mul_f32 v[34:35], v[190:191], v[34:35]
	v_pk_fma_f32 v[32:33], v[232:233], v[32:33], v[156:157]
	v_pk_fma_f32 v[34:35], v[234:235], v[34:35], v[158:159]
	v_cvt_pk_bf16_f32 v32, v32, v33
	v_cvt_pk_bf16_f32 v33, v34, v35
	v_pk_mul_f32 v[8:9], v[8:9], v[214:215] op_sel_hi:[1,0]
	v_pk_mul_f32 v[10:11], v[10:11], v[214:215] op_sel_hi:[1,0]
	v_pk_mul_f32 v[8:9], v[192:193], v[8:9]
	v_pk_mul_f32 v[10:11], v[194:195], v[10:11]
	v_pk_fma_f32 v[8:9], v[236:237], v[8:9], v[160:161]
	v_pk_fma_f32 v[10:11], v[238:239], v[10:11], v[162:163]
	v_cvt_pk_bf16_f32 v8, v8, v9
	v_cvt_pk_bf16_f32 v9, v10, v11
	global_store_dwordx2 v133, v[104:105], s[68:69]
	global_store_dwordx2 v133, v[72:73], s[68:69] offset:32
	global_store_dwordx2 v133, v[32:33], s[68:69] offset:256
	global_store_dwordx2 v133, v[8:9], s[68:69] offset:288
	v_pk_mul_f32 v[92:93], v[92:93], v[216:217] op_sel_hi:[1,0]
	v_pk_mul_f32 v[94:95], v[94:95], v[216:217] op_sel_hi:[1,0]
	v_pk_mul_f32 v[92:93], v[180:181], v[92:93]
	v_pk_mul_f32 v[94:95], v[182:183], v[94:95]
	v_pk_fma_f32 v[92:93], v[220:221], v[92:93], v[240:241]
	v_pk_fma_f32 v[94:95], v[222:223], v[94:95], v[242:243]
	v_cvt_pk_bf16_f32 v92, v92, v93
	v_cvt_pk_bf16_f32 v93, v94, v95
	v_pk_mul_f32 v[60:61], v[60:61], v[216:217] op_sel_hi:[1,0]
	v_pk_mul_f32 v[62:63], v[62:63], v[216:217] op_sel_hi:[1,0]
	v_pk_mul_f32 v[60:61], v[184:185], v[60:61]
	v_pk_mul_f32 v[62:63], v[186:187], v[62:63]
	v_pk_fma_f32 v[60:61], v[224:225], v[60:61], v[244:245]
	v_pk_fma_f32 v[62:63], v[226:227], v[62:63], v[246:247]
	v_cvt_pk_bf16_f32 v60, v60, v61
	v_cvt_pk_bf16_f32 v61, v62, v63
	v_pk_mul_f32 v[24:25], v[24:25], v[216:217] op_sel_hi:[1,0]
	v_pk_mul_f32 v[26:27], v[26:27], v[216:217] op_sel_hi:[1,0]
	v_pk_mul_f32 v[24:25], v[188:189], v[24:25]
	v_pk_mul_f32 v[26:27], v[190:191], v[26:27]
	v_pk_fma_f32 v[24:25], v[232:233], v[24:25], v[156:157]
	v_pk_fma_f32 v[26:27], v[234:235], v[26:27], v[158:159]
	v_cvt_pk_bf16_f32 v24, v24, v25
	v_cvt_pk_bf16_f32 v25, v26, v27
	v_pk_mul_f32 v[4:5], v[4:5], v[216:217] op_sel_hi:[1,0]
	v_pk_mul_f32 v[6:7], v[6:7], v[216:217] op_sel_hi:[1,0]
	v_pk_mul_f32 v[4:5], v[192:193], v[4:5]
	v_pk_mul_f32 v[6:7], v[194:195], v[6:7]
	v_pk_fma_f32 v[4:5], v[236:237], v[4:5], v[160:161]
	v_pk_fma_f32 v[6:7], v[238:239], v[6:7], v[162:163]
	v_cvt_pk_bf16_f32 v4, v4, v5
	v_cvt_pk_bf16_f32 v5, v6, v7
	global_store_dwordx2 v134, v[92:93], s[68:69]
	global_store_dwordx2 v134, v[60:61], s[68:69] offset:32
	global_store_dwordx2 v134, v[24:25], s[68:69] offset:256
	global_store_dwordx2 v134, v[4:5], s[68:69] offset:288
	v_pk_mul_f32 v[84:85], v[84:85], v[218:219] op_sel_hi:[1,0]
	v_pk_mul_f32 v[86:87], v[86:87], v[218:219] op_sel_hi:[1,0]
	v_pk_mul_f32 v[84:85], v[180:181], v[84:85]
	v_pk_mul_f32 v[86:87], v[182:183], v[86:87]
	v_pk_fma_f32 v[84:85], v[220:221], v[84:85], v[240:241]
	v_pk_fma_f32 v[86:87], v[222:223], v[86:87], v[242:243]
	v_cvt_pk_bf16_f32 v84, v84, v85
	v_cvt_pk_bf16_f32 v85, v86, v87
	v_pk_mul_f32 v[56:57], v[56:57], v[218:219] op_sel_hi:[1,0]
	v_pk_mul_f32 v[58:59], v[58:59], v[218:219] op_sel_hi:[1,0]
	v_pk_mul_f32 v[56:57], v[184:185], v[56:57]
	v_pk_mul_f32 v[58:59], v[186:187], v[58:59]
	v_pk_fma_f32 v[56:57], v[224:225], v[56:57], v[244:245]
	v_pk_fma_f32 v[58:59], v[226:227], v[58:59], v[246:247]
	v_cvt_pk_bf16_f32 v56, v56, v57
	v_cvt_pk_bf16_f32 v57, v58, v59
	v_pk_mul_f32 v[16:17], v[16:17], v[218:219] op_sel_hi:[1,0]
	v_pk_mul_f32 v[18:19], v[18:19], v[218:219] op_sel_hi:[1,0]
	v_pk_mul_f32 v[16:17], v[188:189], v[16:17]
	v_pk_mul_f32 v[18:19], v[190:191], v[18:19]
	v_pk_fma_f32 v[16:17], v[232:233], v[16:17], v[156:157]
	v_pk_fma_f32 v[18:19], v[234:235], v[18:19], v[158:159]
	v_cvt_pk_bf16_f32 v16, v16, v17
	v_cvt_pk_bf16_f32 v17, v18, v19
	v_pk_mul_f32 v[0:1], v[0:1], v[218:219] op_sel_hi:[1,0]
	v_pk_mul_f32 v[2:3], v[2:3], v[218:219] op_sel_hi:[1,0]
	v_pk_mul_f32 v[0:1], v[192:193], v[0:1]
	v_pk_mul_f32 v[2:3], v[194:195], v[2:3]
	v_pk_fma_f32 v[0:1], v[236:237], v[0:1], v[160:161]
	v_pk_fma_f32 v[2:3], v[238:239], v[2:3], v[162:163]
	v_cvt_pk_bf16_f32 v0, v0, v1
	v_cvt_pk_bf16_f32 v1, v2, v3
	global_store_dwordx2 v135, v[84:85], s[68:69]
	global_store_dwordx2 v135, v[56:57], s[68:69] offset:32
	global_store_dwordx2 v135, v[16:17], s[68:69] offset:256
	global_store_dwordx2 v135, v[0:1], s[68:69] offset:288
	s_mov_b64 s[38:39], -1
	s_andn2_b64 vcc, exec, s[6:7]
	s_cbranch_vccnz .LBB0_1192
	s_andn2_b64 vcc, exec, s[0:1]
	s_cbranch_vccnz .LBB0_1191
	s_barrier
	s_branch .LBB0_1191

.LBB0_1414:
	v_lshl_add_u32 v128, s66, 8, v218
	v_lshl_or_b32 v136, s67, 8, v220
	s_load_dwordx2 s[18:19], s[92:93], 0xc8
	s_load_dwordx2 s[20:21], s[92:93], 0xd8
	s_ashr_i32 s2, s66, 4
	v_lshlrev_b32_e32 v137, 2, v128
	v_lshlrev_b32_e32 v136, 2, v136
	s_mul_hi_i32 s31, s2, 0x9000
	s_mul_i32 s2, s2, 0x9000
	v_lshl_add_u32 v128, v128, 12, v136
	s_add_u32 s30, s50, s2
	s_addc_u32 s31, s51, s31
	v_add_u32_e32 v129, 0x10000, v128
	v_add_u32_e32 v130, 0x20000, v128
	v_add_u32_e32 v131, 0x30000, v128
	v_add_u32_e32 v132, 0x80000, v128
	v_add_u32_e32 v133, 0x90000, v128
	v_add_u32_e32 v134, 0xa0000, v128
	v_add_u32_e32 v135, 0xb0000, v128
	v_and_b32_e32 v138, 63, v230
	v_xor_b32_e32 v139, 32, v138
	v_xor_b32_e32 v138, 16, v138
	v_lshlrev_b32_e32 v139, 2, v139
	v_lshlrev_b32_e32 v138, 2, v138
	global_load_dwordx4 v[140:143], v136, s[30:31]
	global_load_dwordx4 v[144:147], v136, s[30:31] offset:64
	global_load_dwordx4 v[148:151], v136, s[30:31] offset:512
	global_load_dwordx4 v[152:155], v136, s[30:31] offset:576
	global_load_dwordx4 v[184:187], v128, s[8:9]
	global_load_dwordx4 v[188:191], v128, s[8:9] offset:64
	global_load_dwordx4 v[192:195], v128, s[8:9] offset:512
	global_load_dwordx4 v[196:199], v128, s[8:9] offset:576
	global_load_dwordx4 v[200:203], v129, s[8:9]
	global_load_dwordx4 v[204:207], v129, s[8:9] offset:64
	global_load_dwordx4 v[208:211], v129, s[8:9] offset:512
	global_load_dwordx4 v[212:215], v129, s[8:9] offset:576
	global_load_dwordx4 v[156:159], v130, s[8:9]
	global_load_dwordx4 v[160:163], v130, s[8:9] offset:64
	global_load_dwordx4 v[164:167], v130, s[8:9] offset:512
	global_load_dwordx4 v[168:171], v130, s[8:9] offset:576
	global_load_dwordx4 v[232:235], v131, s[8:9]
	global_load_dwordx4 v[236:239], v131, s[8:9] offset:64
	global_load_dwordx4 v[240:243], v131, s[8:9] offset:512
	global_load_dwordx4 v[244:247], v131, s[8:9] offset:576
	s_waitcnt lgkmcnt(0)
	s_add_u32 s20, s20, 0x32a0000
	s_addc_u32 s21, s21, 0
	s_add_u32 s22, s20, 0x100400
	s_addc_u32 s23, s21, 0
	s_waitcnt vmcnt(8)
	v_pk_mul_f32 v[140:141], v[140:141], 0.5 op_sel_hi:[1,0]
	v_pk_mul_f32 v[142:143], v[142:143], 0.5 op_sel_hi:[1,0]
	v_pk_mul_f32 v[144:145], v[144:145], 0.5 op_sel_hi:[1,0]
	v_pk_mul_f32 v[146:147], v[146:147], 0.5 op_sel_hi:[1,0]
	v_pk_mul_f32 v[148:149], v[148:149], 0.5 op_sel_hi:[1,0]
	v_pk_mul_f32 v[150:151], v[150:151], 0.5 op_sel_hi:[1,0]
	v_pk_mul_f32 v[152:153], v[152:153], 0.5 op_sel_hi:[1,0]
	v_pk_mul_f32 v[154:155], v[154:155], 0.5 op_sel_hi:[1,0]
	v_pk_fma_f32 v[124:125], v[124:125], v[140:141], v[184:185]
	v_pk_fma_f32 v[126:127], v[126:127], v[142:143], v[186:187]
	v_pk_mul_f32 v[216:217], v[124:125], v[124:125]
	v_pk_fma_f32 v[216:217], v[126:127], v[126:127], v[216:217]
	v_pk_fma_f32 v[96:97], v[96:97], v[144:145], v[188:189]
	v_pk_fma_f32 v[98:99], v[98:99], v[146:147], v[190:191]
	v_pk_fma_f32 v[216:217], v[96:97], v[96:97], v[216:217]
	v_pk_fma_f32 v[216:217], v[98:99], v[98:99], v[216:217]
	v_pk_fma_f32 v[64:65], v[64:65], v[148:149], v[192:193]
	v_pk_fma_f32 v[66:67], v[66:67], v[150:151], v[194:195]
	v_pk_fma_f32 v[216:217], v[64:65], v[64:65], v[216:217]
	v_pk_fma_f32 v[216:217], v[66:67], v[66:67], v[216:217]
	v_pk_fma_f32 v[44:45], v[44:45], v[152:153], v[196:197]
	v_pk_fma_f32 v[46:47], v[46:47], v[154:155], v[198:199]
	v_pk_fma_f32 v[216:217], v[44:45], v[44:45], v[216:217]
	v_pk_fma_f32 v[216:217], v[46:47], v[46:47], v[216:217]
	s_nop 0
	v_add_f32_e32 v224, v216, v217
	v_pk_fma_f32 v[120:121], v[120:121], v[140:141], v[200:201]
	v_pk_fma_f32 v[122:123], v[122:123], v[142:143], v[202:203]
	v_pk_mul_f32 v[216:217], v[120:121], v[120:121]
	v_pk_fma_f32 v[216:217], v[122:123], v[122:123], v[216:217]
	v_pk_fma_f32 v[88:89], v[88:89], v[144:145], v[204:205]
	v_pk_fma_f32 v[90:91], v[90:91], v[146:147], v[206:207]
	v_pk_fma_f32 v[216:217], v[88:89], v[88:89], v[216:217]
	v_pk_fma_f32 v[216:217], v[90:91], v[90:91], v[216:217]
	v_pk_fma_f32 v[56:57], v[56:57], v[148:149], v[208:209]
	v_pk_fma_f32 v[58:59], v[58:59], v[150:151], v[210:211]
	v_pk_fma_f32 v[216:217], v[56:57], v[56:57], v[216:217]
	v_pk_fma_f32 v[216:217], v[58:59], v[58:59], v[216:217]
	v_pk_fma_f32 v[36:37], v[36:37], v[152:153], v[212:213]
	v_pk_fma_f32 v[38:39], v[38:39], v[154:155], v[214:215]
	v_pk_fma_f32 v[216:217], v[36:37], v[36:37], v[216:217]
	v_pk_fma_f32 v[216:217], v[38:39], v[38:39], v[216:217]
	s_nop 0
	v_add_f32_e32 v225, v216, v217
	s_nop 1
	global_load_dwordx4 v[184:187], v132, s[8:9]
	global_load_dwordx4 v[188:191], v132, s[8:9] offset:64
	global_load_dwordx4 v[192:195], v132, s[8:9] offset:512
	global_load_dwordx4 v[196:199], v132, s[8:9] offset:576
	global_load_dwordx4 v[200:203], v133, s[8:9]
	global_load_dwordx4 v[204:207], v133, s[8:9] offset:64
	global_load_dwordx4 v[208:211], v133, s[8:9] offset:512
	global_load_dwordx4 v[212:215], v133, s[8:9] offset:576
	s_waitcnt vmcnt(8)
	v_pk_fma_f32 v[116:117], v[116:117], v[140:141], v[156:157]
	v_pk_fma_f32 v[118:119], v[118:119], v[142:143], v[158:159]
	v_pk_mul_f32 v[216:217], v[116:117], v[116:117]
	v_pk_fma_f32 v[216:217], v[118:119], v[118:119], v[216:217]
	v_pk_fma_f32 v[84:85], v[84:85], v[144:145], v[160:161]
	v_pk_fma_f32 v[86:87], v[86:87], v[146:147], v[162:163]
	v_pk_fma_f32 v[216:217], v[84:85], v[84:85], v[216:217]
	v_pk_fma_f32 v[216:217], v[86:87], v[86:87], v[216:217]
	v_pk_fma_f32 v[52:53], v[52:53], v[148:149], v[164:165]
	v_pk_fma_f32 v[54:55], v[54:55], v[150:151], v[166:167]
	v_pk_fma_f32 v[216:217], v[52:53], v[52:53], v[216:217]
	v_pk_fma_f32 v[216:217], v[54:55], v[54:55], v[216:217]
	v_pk_fma_f32 v[28:29], v[28:29], v[152:153], v[168:169]
	v_pk_fma_f32 v[30:31], v[30:31], v[154:155], v[170:171]
	v_pk_fma_f32 v[216:217], v[28:29], v[28:29], v[216:217]
	v_pk_fma_f32 v[216:217], v[30:31], v[30:31], v[216:217]
	s_nop 0
	v_add_f32_e32 v226, v216, v217
	v_pk_fma_f32 v[112:113], v[112:113], v[140:141], v[232:233]
	v_pk_fma_f32 v[114:115], v[114:115], v[142:143], v[234:235]
	v_pk_mul_f32 v[216:217], v[112:113], v[112:113]
	v_pk_fma_f32 v[216:217], v[114:115], v[114:115], v[216:217]
	v_pk_fma_f32 v[80:81], v[80:81], v[144:145], v[236:237]
	v_pk_fma_f32 v[82:83], v[82:83], v[146:147], v[238:239]
	v_pk_fma_f32 v[216:217], v[80:81], v[80:81], v[216:217]
	v_pk_fma_f32 v[216:217], v[82:83], v[82:83], v[216:217]
	v_pk_fma_f32 v[48:49], v[48:49], v[148:149], v[240:241]
	v_pk_fma_f32 v[50:51], v[50:51], v[150:151], v[242:243]
	v_pk_fma_f32 v[216:217], v[48:49], v[48:49], v[216:217]
	v_pk_fma_f32 v[216:217], v[50:51], v[50:51], v[216:217]
	v_pk_fma_f32 v[20:21], v[20:21], v[152:153], v[244:245]
	v_pk_fma_f32 v[22:23], v[22:23], v[154:155], v[246:247]
	v_pk_fma_f32 v[216:217], v[20:21], v[20:21], v[216:217]
	v_pk_fma_f32 v[216:217], v[22:23], v[22:23], v[216:217]
	s_nop 0
	v_add_f32_e32 v227, v216, v217
	s_nop 1
	global_load_dwordx4 v[156:159], v134, s[8:9]
	global_load_dwordx4 v[160:163], v134, s[8:9] offset:64
	global_load_dwordx4 v[164:167], v134, s[8:9] offset:512
	global_load_dwordx4 v[168:171], v134, s[8:9] offset:576
	global_load_dwordx4 v[232:235], v135, s[8:9]
	global_load_dwordx4 v[236:239], v135, s[8:9] offset:64
	global_load_dwordx4 v[240:243], v135, s[8:9] offset:512
	global_load_dwordx4 v[244:247], v135, s[8:9] offset:576
	s_waitcnt vmcnt(8)
	v_pk_fma_f32 v[108:109], v[108:109], v[140:141], v[184:185]
	v_pk_fma_f32 v[110:111], v[110:111], v[142:143], v[186:187]
	v_pk_mul_f32 v[216:217], v[108:109], v[108:109]
	v_pk_fma_f32 v[216:217], v[110:111], v[110:111], v[216:217]
	v_pk_fma_f32 v[76:77], v[76:77], v[144:145], v[188:189]
	v_pk_fma_f32 v[78:79], v[78:79], v[146:147], v[190:191]
	v_pk_fma_f32 v[216:217], v[76:77], v[76:77], v[216:217]
	v_pk_fma_f32 v[216:217], v[78:79], v[78:79], v[216:217]
	v_pk_fma_f32 v[40:41], v[40:41], v[148:149], v[192:193]
	v_pk_fma_f32 v[42:43], v[42:43], v[150:151], v[194:195]
	v_pk_fma_f32 v[216:217], v[40:41], v[40:41], v[216:217]
	v_pk_fma_f32 v[216:217], v[42:43], v[42:43], v[216:217]
	v_pk_fma_f32 v[12:13], v[12:13], v[152:153], v[196:197]
	v_pk_fma_f32 v[14:15], v[14:15], v[154:155], v[198:199]
	v_pk_fma_f32 v[216:217], v[12:13], v[12:13], v[216:217]
	v_pk_fma_f32 v[216:217], v[14:15], v[14:15], v[216:217]
	s_nop 0
	v_add_f32_e32 v228, v216, v217
	v_pk_fma_f32 v[104:105], v[104:105], v[140:141], v[200:201]
	v_pk_fma_f32 v[106:107], v[106:107], v[142:143], v[202:203]
	v_pk_mul_f32 v[216:217], v[104:105], v[104:105]
	v_pk_fma_f32 v[216:217], v[106:107], v[106:107], v[216:217]
	v_pk_fma_f32 v[72:73], v[72:73], v[144:145], v[204:205]
	v_pk_fma_f32 v[74:75], v[74:75], v[146:147], v[206:207]
	v_pk_fma_f32 v[216:217], v[72:73], v[72:73], v[216:217]
	v_pk_fma_f32 v[216:217], v[74:75], v[74:75], v[216:217]
	v_pk_fma_f32 v[32:33], v[32:33], v[148:149], v[208:209]
	v_pk_fma_f32 v[34:35], v[34:35], v[150:151], v[210:211]
	v_pk_fma_f32 v[216:217], v[32:33], v[32:33], v[216:217]
	v_pk_fma_f32 v[216:217], v[34:35], v[34:35], v[216:217]
	v_pk_fma_f32 v[8:9], v[8:9], v[152:153], v[212:213]
	v_pk_fma_f32 v[10:11], v[10:11], v[154:155], v[214:215]
	v_pk_fma_f32 v[216:217], v[8:9], v[8:9], v[216:217]
	v_pk_fma_f32 v[216:217], v[10:11], v[10:11], v[216:217]
	s_nop 0
	v_add_f32_e32 v229, v216, v217
	s_nop 1
	global_load_dwordx4 v[184:187], v136, s[18:19]
	global_load_dwordx4 v[188:191], v136, s[18:19] offset:64
	global_load_dwordx4 v[192:195], v136, s[18:19] offset:512
	global_load_dwordx4 v[196:199], v136, s[18:19] offset:576
	s_waitcnt vmcnt(4)
	v_pk_fma_f32 v[100:101], v[100:101], v[140:141], v[156:157]
	v_pk_fma_f32 v[102:103], v[102:103], v[142:143], v[158:159]
	v_pk_mul_f32 v[216:217], v[100:101], v[100:101]
	v_pk_fma_f32 v[216:217], v[102:103], v[102:103], v[216:217]
	v_pk_fma_f32 v[68:69], v[68:69], v[144:145], v[160:161]
	v_pk_fma_f32 v[70:71], v[70:71], v[146:147], v[162:163]
	v_pk_fma_f32 v[216:217], v[68:69], v[68:69], v[216:217]
	v_pk_fma_f32 v[216:217], v[70:71], v[70:71], v[216:217]
	v_pk_fma_f32 v[24:25], v[24:25], v[148:149], v[164:165]
	v_pk_fma_f32 v[26:27], v[26:27], v[150:151], v[166:167]
	v_pk_fma_f32 v[216:217], v[24:25], v[24:25], v[216:217]
	v_pk_fma_f32 v[216:217], v[26:27], v[26:27], v[216:217]
	v_pk_fma_f32 v[4:5], v[4:5], v[152:153], v[168:169]
	v_pk_fma_f32 v[6:7], v[6:7], v[154:155], v[170:171]
	v_pk_fma_f32 v[216:217], v[4:5], v[4:5], v[216:217]
	v_pk_fma_f32 v[216:217], v[6:7], v[6:7], v[216:217]
	s_nop 0
	v_add_f32_e32 v248, v216, v217
	v_pk_fma_f32 v[92:93], v[92:93], v[140:141], v[232:233]
	v_pk_fma_f32 v[94:95], v[94:95], v[142:143], v[234:235]
	v_pk_mul_f32 v[216:217], v[92:93], v[92:93]
	v_pk_fma_f32 v[216:217], v[94:95], v[94:95], v[216:217]
	v_pk_fma_f32 v[60:61], v[60:61], v[144:145], v[236:237]
	v_pk_fma_f32 v[62:63], v[62:63], v[146:147], v[238:239]
	v_pk_fma_f32 v[216:217], v[60:61], v[60:61], v[216:217]
	v_pk_fma_f32 v[216:217], v[62:63], v[62:63], v[216:217]
	v_pk_fma_f32 v[16:17], v[16:17], v[148:149], v[240:241]
	v_pk_fma_f32 v[18:19], v[18:19], v[150:151], v[242:243]
	v_pk_fma_f32 v[216:217], v[16:17], v[16:17], v[216:217]
	v_pk_fma_f32 v[216:217], v[18:19], v[18:19], v[216:217]
	v_pk_fma_f32 v[0:1], v[0:1], v[152:153], v[244:245]
	v_pk_fma_f32 v[2:3], v[2:3], v[154:155], v[246:247]
	v_pk_fma_f32 v[216:217], v[0:1], v[0:1], v[216:217]
	v_pk_fma_f32 v[216:217], v[2:3], v[2:3], v[216:217]
	s_nop 0
	v_add_f32_e32 v249, v216, v217
	ds_bpermute_b32 v200, v138, v224
	ds_bpermute_b32 v201, v138, v225
	ds_bpermute_b32 v202, v138, v226
	ds_bpermute_b32 v203, v138, v227
	ds_bpermute_b32 v204, v138, v228
	ds_bpermute_b32 v205, v138, v229
	ds_bpermute_b32 v206, v138, v248
	ds_bpermute_b32 v207, v138, v249
	s_waitcnt lgkmcnt(0)
	v_add_f32_e32 v224, v224, v200
	v_add_f32_e32 v225, v225, v201
	v_add_f32_e32 v226, v226, v202
	v_add_f32_e32 v227, v227, v203
	v_add_f32_e32 v228, v228, v204
	v_add_f32_e32 v229, v229, v205
	v_add_f32_e32 v248, v248, v206
	v_add_f32_e32 v249, v249, v207
	ds_bpermute_b32 v200, v139, v224
	ds_bpermute_b32 v201, v139, v225
	ds_bpermute_b32 v202, v139, v226
	ds_bpermute_b32 v203, v139, v227
	ds_bpermute_b32 v204, v139, v228
	ds_bpermute_b32 v205, v139, v229
	ds_bpermute_b32 v206, v139, v248
	ds_bpermute_b32 v207, v139, v249
	s_waitcnt lgkmcnt(0)
	v_add_f32_e32 v224, v224, v200
	v_add_f32_e32 v225, v225, v201
	v_add_f32_e32 v226, v226, v202
	v_add_f32_e32 v227, v227, v203
	v_add_f32_e32 v228, v228, v204
	v_add_f32_e32 v229, v229, v205
	v_add_f32_e32 v248, v248, v206
	v_add_f32_e32 v249, v249, v207
	v_lshrrev_b32_e32 v140, 5, v220
	v_and_b32_e32 v140, 3, v140
	v_lshlrev_b32_e32 v142, 4, v218
	v_add_u32_e32 v142, 0x20400, v142
	v_lshl_add_u32 v141, v140, 2, v142
	v_lshl_add_u32 v144, s66, 8, v218
	v_lshlrev_b32_e32 v144, 4, v144
	v_mov_b32_e32 v143, s67
	v_lshl_add_u32 v143, v143, 2, v144
	s_mov_b64 exec, 0xffff
	ds_write_b32 v141, v224
	ds_write_b32 v141, v225 offset:256
	ds_write_b32 v141, v226 offset:512
	ds_write_b32 v141, v227 offset:768
	ds_write_b32 v141, v228 offset:2048
	ds_write_b32 v141, v229 offset:2304
	ds_write_b32 v141, v248 offset:2560
	ds_write_b32 v141, v249 offset:2816
	s_mov_b64 exec, -1
	s_waitcnt lgkmcnt(0)
	s_barrier
	ds_read_b128 v[156:159], v142
	ds_read_b128 v[160:163], v142 offset:256
	ds_read_b128 v[164:167], v142 offset:512
	ds_read_b128 v[168:171], v142 offset:768
	ds_read_b128 v[232:235], v142 offset:2048
	ds_read_b128 v[236:239], v142 offset:2304
	ds_read_b128 v[240:243], v142 offset:2560
	ds_read_b128 v[244:247], v142 offset:2816
	s_waitcnt lgkmcnt(0)
	v_add_f32_e32 v250, v156, v157
	v_add_f32_e32 v251, v158, v159
	v_add_f32_e32 v224, v250, v251
	v_add_f32_e32 v250, v160, v161
	v_add_f32_e32 v251, v162, v163
	v_add_f32_e32 v225, v250, v251
	v_add_f32_e32 v250, v164, v165
	v_add_f32_e32 v251, v166, v167
	v_add_f32_e32 v226, v250, v251
	v_add_f32_e32 v250, v168, v169
	v_add_f32_e32 v251, v170, v171
	v_add_f32_e32 v227, v250, v251
	v_add_f32_e32 v250, v232, v233
	v_add_f32_e32 v251, v234, v235
	v_add_f32_e32 v228, v250, v251
	v_add_f32_e32 v250, v236, v237
	v_add_f32_e32 v251, v238, v239
	v_add_f32_e32 v229, v250, v251
	v_add_f32_e32 v250, v240, v241
	v_add_f32_e32 v251, v242, v243
	v_add_f32_e32 v248, v250, v251
	v_add_f32_e32 v250, v244, v245
	v_add_f32_e32 v251, v246, v247
	v_add_f32_e32 v249, v250, v251
	v_readfirstlane_b32 s26, v140
	s_nop 0
	s_cmp_lg_u32 s26, 0
	s_cbranch_scc1 .Lfn_nosw_p14
	s_mov_b64 exec, 0xffff
	global_atomic_swap v143, v224, s[20:21]
	global_atomic_swap v143, v225, s[20:21] offset:256
	global_atomic_swap v143, v226, s[20:21] offset:512
	global_atomic_swap v143, v227, s[20:21] offset:768
	global_atomic_swap v143, v228, s[20:21] offset:2048
	global_atomic_swap v143, v229, s[20:21] offset:2304
	global_atomic_swap v143, v248, s[20:21] offset:2560
	global_atomic_swap v143, v249, s[20:21] offset:2816
	s_mov_b64 exec, -1
